# peeled-last-iteration GEMM loops plus phase C pk_mul+add -> v_fma_f32 fusion (143 sites)
# baseline (speedup 1.0000x reference)
.LBB0_405:
	s_cmpk_gt_i32 s30, 0xcbf
	s_mov_b64 s[0:1], -1
	s_cbranch_scc0 .LBB0_426
	s_cmpk_gt_u32 s30, 0x197f
	s_cbranch_scc0 .LBB0_418
	s_waitcnt vmcnt(0)
	v_mov_b32_e32 v95, v179
	s_add_i32 s10, s30, 0xffffe680
	s_nop 0
	v_and_b32_e32 v1, 15, v95
	v_lshlrev_b32_e32 v2, 5, v95
	v_lshl_add_u32 v0, s10, 8, v95
	v_and_b32_e32 v2, 0x100, v2
	v_cmp_gt_u32_e32 vcc, 4, v1
	v_ashrrev_i32_e32 v0, 4, v0
	s_waitcnt lgkmcnt(0)
	v_lshlrev_b32_e32 v4, 6, v1
	v_cndmask_b32_e64 v5, v2, 0, vcc
	v_mov_b64_e32 v[2:3], s[66:67]
	v_mad_i64_i32 v[2:3], s[0:1], v0, s43, v[2:3]
	v_add_lshl_u32 v176, v5, v4, 1
	v_lshl_add_u64 v[30:31], v[2:3], 0, v[176:177]
	global_load_dwordx4 v[2:5], v[30:31], off
	global_load_dwordx4 v[6:9], v[30:31], off offset:16
	global_load_dwordx4 v[10:13], v[30:31], off offset:32
	global_load_dwordx4 v[14:17], v[30:31], off offset:48
	global_load_dwordx4 v[18:21], v[30:31], off offset:64
	global_load_dwordx4 v[22:25], v[30:31], off offset:80
	global_load_dwordx4 v[36:39], v[30:31], off offset:96
	global_load_dwordx4 v[96:99], v[30:31], off offset:112
	v_cmp_gt_i32_e64 s[0:1], s39, v0
	v_cmp_lt_u32_e64 s[4:5], 7, v1
	s_waitcnt vmcnt(7)
	v_and_b32_e32 v93, 0xffff0000, v2
	v_lshlrev_b32_e32 v92, 16, v2
	v_and_b32_e32 v91, 0xffff0000, v3
	v_lshlrev_b32_e32 v90, 16, v3
	v_and_b32_e32 v89, 0xffff0000, v4
	v_lshlrev_b32_e32 v88, 16, v4
	v_and_b32_e32 v87, 0xffff0000, v5
	v_lshlrev_b32_e32 v86, 16, v5
	s_waitcnt vmcnt(6)
	v_and_b32_e32 v69, 0xffff0000, v6
	v_lshlrev_b32_e32 v68, 16, v6
	s_waitcnt vmcnt(5)
	v_and_b32_e32 v85, 0xffff0000, v10
	v_lshlrev_b32_e32 v84, 16, v10
	s_waitcnt vmcnt(4)
	v_and_b32_e32 v45, 0xffff0000, v14
	v_lshlrev_b32_e32 v44, 16, v14
	v_and_b32_e32 v71, 0xffff0000, v7
	v_lshlrev_b32_e32 v70, 16, v7
	v_and_b32_e32 v83, 0xffff0000, v11
	v_lshlrev_b32_e32 v82, 16, v11
	v_and_b32_e32 v49, 0xffff0000, v15
	v_lshlrev_b32_e32 v48, 16, v15
	v_and_b32_e32 v73, 0xffff0000, v8
	v_lshlrev_b32_e32 v72, 16, v8
	v_and_b32_e32 v79, 0xffff0000, v12
	v_lshlrev_b32_e32 v78, 16, v12
	v_and_b32_e32 v59, 0xffff0000, v16
	v_lshlrev_b32_e32 v58, 16, v16
	v_and_b32_e32 v75, 0xffff0000, v9
	v_lshlrev_b32_e32 v74, 16, v9
	v_and_b32_e32 v77, 0xffff0000, v13
	v_lshlrev_b32_e32 v76, 16, v13
	v_and_b32_e32 v61, 0xffff0000, v17
	v_lshlrev_b32_e32 v60, 16, v17
	s_waitcnt vmcnt(3)
	v_and_b32_e32 v81, 0xffff0000, v18
	v_lshlrev_b32_e32 v80, 16, v18
	v_and_b32_e32 v53, 0xffff0000, v19
	v_lshlrev_b32_e32 v52, 16, v19
	v_and_b32_e32 v55, 0xffff0000, v20
	v_lshlrev_b32_e32 v54, 16, v20
	v_and_b32_e32 v57, 0xffff0000, v21
	v_lshlrev_b32_e32 v56, 16, v21
	s_waitcnt vmcnt(2)
	v_and_b32_e32 v47, 0xffff0000, v22
	v_lshlrev_b32_e32 v46, 16, v22
	s_waitcnt vmcnt(1)
	v_and_b32_e32 v27, 0xffff0000, v36
	v_lshlrev_b32_e32 v26, 16, v36
	s_waitcnt vmcnt(0)
	v_and_b32_e32 v33, 0xffff0000, v96
	v_lshlrev_b32_e32 v32, 16, v96
	v_and_b32_e32 v63, 0xffff0000, v23
	v_lshlrev_b32_e32 v62, 16, v23
	v_and_b32_e32 v41, 0xffff0000, v37
	v_lshlrev_b32_e32 v40, 16, v37
	v_and_b32_e32 v35, 0xffff0000, v97
	v_lshlrev_b32_e32 v34, 16, v97
	v_and_b32_e32 v65, 0xffff0000, v24
	v_lshlrev_b32_e32 v64, 16, v24
	v_and_b32_e32 v43, 0xffff0000, v38
	v_lshlrev_b32_e32 v42, 16, v38
	v_and_b32_e32 v37, 0xffff0000, v98
	v_lshlrev_b32_e32 v36, 16, v98
	v_and_b32_e32 v67, 0xffff0000, v25
	v_lshlrev_b32_e32 v66, 16, v25
	v_and_b32_e32 v51, 0xffff0000, v39
	v_lshlrev_b32_e32 v50, 16, v39
	v_and_b32_e32 v39, 0xffff0000, v99
	v_lshlrev_b32_e32 v38, 16, v99
	v_bfe_u32 v99, v0, 6, 6
	v_and_b32_e32 v98, 63, v0
	s_and_saveexec_b64 s[2:3], s[4:5]
	s_xor_b64 s[2:3], exec, s[2:3]
	s_cbranch_execz .LBB0_411
	v_pk_mul_f32 v[2:3], v[92:93], v[92:93]
	v_add_f32_e32 v0, v2, v3
	v_fma_f32 v0, v90, v90, v0
	v_fma_f32 v0, v91, v91, v0
	v_fma_f32 v0, v88, v88, v0
	v_fma_f32 v0, v89, v89, v0
	v_fma_f32 v0, v86, v86, v0
	v_fma_f32 v0, v87, v87, v0
	v_fma_f32 v0, v68, v68, v0
	v_fma_f32 v0, v69, v69, v0
	v_fma_f32 v0, v70, v70, v0
	v_fma_f32 v0, v71, v71, v0
	v_fma_f32 v0, v72, v72, v0
	v_fma_f32 v0, v73, v73, v0
	v_fma_f32 v0, v74, v74, v0
	v_fma_f32 v0, v75, v75, v0
	v_fma_f32 v0, v84, v84, v0
	v_fma_f32 v0, v85, v85, v0
	v_fma_f32 v0, v82, v82, v0
	v_fma_f32 v0, v83, v83, v0
	v_fma_f32 v0, v78, v78, v0
	v_fma_f32 v0, v79, v79, v0
	v_fma_f32 v0, v76, v76, v0
	v_fma_f32 v0, v77, v77, v0
	v_fma_f32 v0, v44, v44, v0
	v_fma_f32 v0, v45, v45, v0
	v_fma_f32 v0, v48, v48, v0
	v_fma_f32 v0, v49, v49, v0
	v_fma_f32 v0, v58, v58, v0
	v_fma_f32 v0, v59, v59, v0
	v_fma_f32 v0, v60, v60, v0
	v_fma_f32 v0, v61, v61, v0
	v_fma_f32 v0, v80, v80, v0
	v_fma_f32 v0, v81, v81, v0
	v_fma_f32 v0, v52, v52, v0
	v_pk_mul_f32 v[108:109], v[54:55], v[54:55]
	v_fma_f32 v0, v53, v53, v0
	v_add_f32_e32 v0, v108, v0
	v_pk_mul_f32 v[110:111], v[56:57], v[56:57]
	v_add_f32_e32 v0, v109, v0
	v_add_f32_e32 v0, v110, v0
	v_pk_mul_f32 v[112:113], v[46:47], v[46:47]
	v_add_f32_e32 v0, v111, v0
	v_add_f32_e32 v0, v112, v0
	v_pk_mul_f32 v[114:115], v[62:63], v[62:63]
	v_add_f32_e32 v0, v113, v0
	v_add_f32_e32 v0, v114, v0
	v_pk_mul_f32 v[116:117], v[64:65], v[64:65]
	v_add_f32_e32 v0, v115, v0
	v_add_f32_e32 v0, v116, v0
	v_pk_mul_f32 v[118:119], v[66:67], v[66:67]
	v_add_f32_e32 v0, v117, v0
	v_add_f32_e32 v0, v118, v0
	v_pk_mul_f32 v[120:121], v[26:27], v[26:27]
	v_add_f32_e32 v0, v119, v0
	v_add_f32_e32 v0, v120, v0
	v_pk_mul_f32 v[122:123], v[40:41], v[40:41]
	v_add_f32_e32 v0, v121, v0
	v_add_f32_e32 v0, v122, v0
	v_pk_mul_f32 v[124:125], v[42:43], v[42:43]
	v_add_f32_e32 v0, v123, v0
	v_add_f32_e32 v0, v124, v0
	v_pk_mul_f32 v[126:127], v[50:51], v[50:51]
	v_add_f32_e32 v0, v125, v0
	v_add_f32_e32 v0, v126, v0
	v_pk_mul_f32 v[128:129], v[32:33], v[32:33]
	v_add_f32_e32 v0, v127, v0
	v_add_f32_e32 v0, v128, v0
	v_pk_mul_f32 v[130:131], v[34:35], v[34:35]
	v_add_f32_e32 v0, v129, v0
	v_add_f32_e32 v0, v130, v0
	v_pk_mul_f32 v[132:133], v[36:37], v[36:37]
	v_add_f32_e32 v0, v131, v0
	v_add_f32_e32 v0, v132, v0
	v_pk_mul_f32 v[134:135], v[38:39], v[38:39]
	v_add_f32_e32 v0, v133, v0
	v_add_f32_e32 v0, v134, v0
	v_add_f32_e32 v0, v135, v0
	v_fmamk_f32 v0, v0, 0x3c800000, v178
	v_cmp_gt_f32_e64 s[4:5], s40, v0
	v_mul_f32_e32 v2, 0x4b800000, v0
	v_readlane_b32 s12, v253, 52
	v_cndmask_b32_e64 v0, v0, v2, s[4:5]
	v_rsq_f32_e32 v0, v0
	v_readlane_b32 s17, v253, 57
	v_readlane_b32 s19, v253, 59
	v_readlane_b32 s16, v253, 56
	v_mul_f32_e32 v2, 0x45800000, v0
	v_cndmask_b32_e64 v94, v0, v2, s[4:5]
	v_cmp_gt_u32_e64 s[4:5], 14, v1
	v_readlane_b32 s18, v253, 58
	v_mov_b32_e32 v0, s19
	v_mov_b32_e32 v1, s17
	v_cndmask_b32_e64 v1, v0, v1, s[4:5]
	v_mov_b32_e32 v0, s18
	v_mov_b32_e32 v2, s16
	v_cndmask_b32_e64 v0, v0, v2, s[4:5]
	v_lshl_add_u64 v[28:29], s[6:7], 2, v[0:1]
	global_load_dwordx4 v[0:3], v[28:29], off offset:48
	global_load_dwordx4 v[4:7], v[28:29], off offset:32
	global_load_dwordx4 v[8:11], v[28:29], off offset:16
	global_load_dwordx4 v[12:15], v[28:29], off
	v_pk_mul_f32 v[16:17], v[94:95], v[92:93] op_sel_hi:[0,1]
	v_pk_mul_f32 v[96:97], v[94:95], v[26:27] op_sel_hi:[0,1]
	v_pk_mul_f32 v[52:53], v[94:95], v[52:53] op_sel_hi:[0,1]
	v_readlane_b32 s13, v253, 53
	v_readlane_b32 s14, v253, 54
	v_readlane_b32 s15, v253, 55
	v_readlane_b32 s20, v253, 60
	v_readlane_b32 s21, v253, 61
	v_readlane_b32 s22, v253, 62
	v_readlane_b32 s23, v253, 63
	v_readlane_b32 s24, v254, 0
	v_readlane_b32 s25, v254, 1
	v_readlane_b32 s26, v254, 2
	v_readlane_b32 s27, v254, 3
	s_waitcnt vmcnt(0)
	v_pk_mul_f32 v[92:93], v[16:17], v[12:13]
	global_load_dwordx4 v[16:19], v[28:29], off offset:112
	global_load_dwordx4 v[20:23], v[28:29], off offset:96
	global_load_dwordx4 v[100:103], v[28:29], off offset:80
	global_load_dwordx4 v[104:107], v[28:29], off offset:64
	v_pk_mul_f32 v[12:13], v[94:95], v[84:85] op_sel_hi:[0,1]
	s_waitcnt vmcnt(0)
	v_pk_mul_f32 v[84:85], v[12:13], v[104:105]
	v_pk_mul_f32 v[12:13], v[94:95], v[90:91] op_sel_hi:[0,1]
	v_pk_mul_f32 v[90:91], v[12:13], v[14:15]
	v_pk_mul_f32 v[12:13], v[94:95], v[82:83] op_sel_hi:[0,1]
	v_pk_mul_f32 v[82:83], v[12:13], v[106:107]
	v_pk_mul_f32 v[12:13], v[94:95], v[88:89] op_sel_hi:[0,1]
	v_pk_mul_f32 v[88:89], v[12:13], v[8:9]
	v_pk_mul_f32 v[8:9], v[94:95], v[78:79] op_sel_hi:[0,1]
	v_pk_mul_f32 v[78:79], v[8:9], v[100:101]
	v_pk_mul_f32 v[8:9], v[94:95], v[86:87] op_sel_hi:[0,1]
	v_pk_mul_f32 v[86:87], v[8:9], v[10:11]
	v_pk_mul_f32 v[8:9], v[94:95], v[76:77] op_sel_hi:[0,1]
	v_pk_mul_f32 v[76:77], v[8:9], v[102:103]
	v_pk_mul_f32 v[8:9], v[94:95], v[68:69] op_sel_hi:[0,1]
	v_pk_mul_f32 v[68:69], v[8:9], v[4:5]
	v_pk_mul_f32 v[4:5], v[94:95], v[44:45] op_sel_hi:[0,1]
	v_pk_mul_f32 v[44:45], v[4:5], v[20:21]
	v_pk_mul_f32 v[4:5], v[94:95], v[70:71] op_sel_hi:[0,1]
	v_pk_mul_f32 v[70:71], v[4:5], v[6:7]
	v_pk_mul_f32 v[4:5], v[94:95], v[48:49] op_sel_hi:[0,1]
	v_pk_mul_f32 v[48:49], v[4:5], v[22:23]
	v_pk_mul_f32 v[4:5], v[94:95], v[72:73] op_sel_hi:[0,1]
	v_pk_mul_f32 v[72:73], v[4:5], v[0:1]
	v_pk_mul_f32 v[0:1], v[94:95], v[58:59] op_sel_hi:[0,1]
	v_pk_mul_f32 v[58:59], v[0:1], v[16:17]
	v_pk_mul_f32 v[0:1], v[94:95], v[74:75] op_sel_hi:[0,1]
	v_pk_mul_f32 v[74:75], v[0:1], v[2:3]
	v_pk_mul_f32 v[0:1], v[94:95], v[60:61] op_sel_hi:[0,1]
	v_pk_mul_f32 v[60:61], v[0:1], v[18:19]
	global_load_dwordx4 v[0:3], v[28:29], off offset:176
	global_load_dwordx4 v[4:7], v[28:29], off offset:160
	global_load_dwordx4 v[8:11], v[28:29], off offset:144
	global_load_dwordx4 v[18:21], v[28:29], off offset:128
	v_pk_mul_f32 v[12:13], v[94:95], v[80:81] op_sel_hi:[0,1]
	s_waitcnt vmcnt(0)
	v_pk_mul_f32 v[80:81], v[12:13], v[18:19]
	global_load_dwordx4 v[12:15], v[28:29], off offset:240
	global_load_dwordx4 v[16:19], v[28:29], off offset:224
	global_load_dwordx4 v[22:25], v[28:29], off offset:208
	s_nop 0
	global_load_dwordx4 v[26:29], v[28:29], off offset:192
	v_pk_mul_f32 v[52:53], v[52:53], v[20:21]
	v_pk_mul_f32 v[20:21], v[94:95], v[40:41] op_sel_hi:[0,1]
	s_waitcnt vmcnt(0)
	v_pk_mul_f32 v[40:41], v[20:21], v[28:29]
	v_pk_mul_f32 v[20:21], v[94:95], v[54:55] op_sel_hi:[0,1]
	v_pk_mul_f32 v[54:55], v[20:21], v[8:9]
	v_pk_mul_f32 v[8:9], v[94:95], v[42:43] op_sel_hi:[0,1]
	v_pk_mul_f32 v[42:43], v[8:9], v[22:23]
	v_pk_mul_f32 v[8:9], v[94:95], v[56:57] op_sel_hi:[0,1]
	v_pk_mul_f32 v[56:57], v[8:9], v[10:11]
	v_pk_mul_f32 v[8:9], v[94:95], v[50:51] op_sel_hi:[0,1]
	v_pk_mul_f32 v[50:51], v[8:9], v[24:25]
	v_pk_mul_f32 v[8:9], v[94:95], v[46:47] op_sel_hi:[0,1]
	v_pk_mul_f32 v[46:47], v[8:9], v[4:5]
	v_pk_mul_f32 v[4:5], v[94:95], v[32:33] op_sel_hi:[0,1]
	v_pk_mul_f32 v[32:33], v[4:5], v[16:17]
	v_pk_mul_f32 v[4:5], v[94:95], v[62:63] op_sel_hi:[0,1]
	v_pk_mul_f32 v[62:63], v[4:5], v[6:7]
	v_pk_mul_f32 v[4:5], v[94:95], v[34:35] op_sel_hi:[0,1]
	v_pk_mul_f32 v[34:35], v[4:5], v[18:19]
	v_pk_mul_f32 v[4:5], v[94:95], v[64:65] op_sel_hi:[0,1]
	v_pk_mul_f32 v[64:65], v[4:5], v[0:1]
	v_pk_mul_f32 v[0:1], v[94:95], v[36:37] op_sel_hi:[0,1]
	v_pk_mul_f32 v[36:37], v[0:1], v[12:13]
	v_pk_mul_f32 v[0:1], v[94:95], v[66:67] op_sel_hi:[0,1]
	v_pk_mul_f32 v[66:67], v[0:1], v[2:3]
	v_pk_mul_f32 v[0:1], v[94:95], v[38:39] op_sel_hi:[0,1]
	v_pk_mul_f32 v[26:27], v[96:97], v[26:27]
	v_pk_mul_f32 v[38:39], v[0:1], v[14:15]
	s_and_saveexec_b64 s[8:9], s[0:1]
	s_cbranch_execz .LBB0_410
	v_lshlrev_b32_e32 v18, 7, v99
	global_load_dwordx4 v[0:3], v18, s[60:61] offset:48
	global_load_dwordx4 v[4:7], v18, s[60:61] offset:32
	global_load_dwordx4 v[8:11], v18, s[60:61] offset:16
	global_load_dwordx4 v[12:15], v18, s[60:61]
	s_waitcnt vmcnt(0)
	v_mov_b32_e32 v17, v14
	v_mov_b32_e32 v14, v13
	v_mov_b32_e32 v16, v12
	v_pk_mul_f32 v[12:13], v[92:93], v[14:15]
	v_pk_mul_f32 v[14:15], v[84:85], v[14:15]
	v_pk_fma_f32 v[84:85], v[84:85], v[16:17], v[12:13]
	v_mov_b32_e32 v13, v10
	v_mov_b32_e32 v10, v9
	v_mov_b32_e32 v12, v8
	v_pk_mul_f32 v[8:9], v[90:91], v[10:11]
	v_pk_mul_f32 v[10:11], v[82:83], v[10:11]
	v_pk_fma_f32 v[82:83], v[82:83], v[12:13], v[8:9]
	v_mov_b32_e32 v9, v6
	v_mov_b32_e32 v6, v5
	v_mov_b32_e32 v8, v4
	v_pk_mul_f32 v[4:5], v[88:89], v[6:7]
	v_pk_mul_f32 v[6:7], v[78:79], v[6:7]
	v_pk_fma_f32 v[78:79], v[78:79], v[8:9], v[4:5]
	v_mov_b32_e32 v5, v2
	v_mov_b32_e32 v2, v1
	v_mov_b32_e32 v4, v0
	v_pk_mul_f32 v[0:1], v[86:87], v[2:3]
	v_pk_mul_f32 v[2:3], v[76:77], v[2:3]
	v_pk_fma_f32 v[92:93], v[92:93], v[16:17], v[14:15] neg_lo:[0,0,1] neg_hi:[0,0,1]
	v_pk_fma_f32 v[90:91], v[90:91], v[12:13], v[10:11] neg_lo:[0,0,1] neg_hi:[0,0,1]
	v_pk_fma_f32 v[88:89], v[88:89], v[8:9], v[6:7] neg_lo:[0,0,1] neg_hi:[0,0,1]
	v_pk_fma_f32 v[86:87], v[86:87], v[4:5], v[2:3] neg_lo:[0,0,1] neg_hi:[0,0,1]
	v_pk_fma_f32 v[76:77], v[76:77], v[4:5], v[0:1]
	global_load_dwordx4 v[0:3], v18, s[60:61] offset:112
	global_load_dwordx4 v[4:7], v18, s[60:61] offset:96
	global_load_dwordx4 v[8:11], v18, s[60:61] offset:80
	global_load_dwordx4 v[12:15], v18, s[60:61] offset:64
	v_lshlrev_b32_e32 v18, 7, v98
	s_waitcnt vmcnt(0)
	v_mov_b32_e32 v17, v14
	v_mov_b32_e32 v14, v13
	v_mov_b32_e32 v16, v12
	v_pk_mul_f32 v[12:13], v[68:69], v[14:15]
	v_pk_mul_f32 v[14:15], v[44:45], v[14:15]
	v_pk_fma_f32 v[44:45], v[44:45], v[16:17], v[12:13]
	v_mov_b32_e32 v13, v10
	v_mov_b32_e32 v10, v9
	v_mov_b32_e32 v12, v8
	v_pk_mul_f32 v[8:9], v[70:71], v[10:11]
	v_pk_mul_f32 v[10:11], v[48:49], v[10:11]
	v_pk_fma_f32 v[48:49], v[48:49], v[12:13], v[8:9]
	v_mov_b32_e32 v9, v6
	v_mov_b32_e32 v6, v5
	v_mov_b32_e32 v8, v4
	v_pk_mul_f32 v[4:5], v[72:73], v[6:7]
	v_pk_mul_f32 v[6:7], v[58:59], v[6:7]
	v_pk_fma_f32 v[58:59], v[58:59], v[8:9], v[4:5]
	v_mov_b32_e32 v5, v2
	v_mov_b32_e32 v2, v1
	v_mov_b32_e32 v4, v0
	v_pk_mul_f32 v[0:1], v[74:75], v[2:3]
	v_pk_mul_f32 v[2:3], v[60:61], v[2:3]
	v_pk_fma_f32 v[68:69], v[68:69], v[16:17], v[14:15] neg_lo:[0,0,1] neg_hi:[0,0,1]
	v_pk_fma_f32 v[70:71], v[70:71], v[12:13], v[10:11] neg_lo:[0,0,1] neg_hi:[0,0,1]
	v_pk_fma_f32 v[72:73], v[72:73], v[8:9], v[6:7] neg_lo:[0,0,1] neg_hi:[0,0,1]
	v_pk_fma_f32 v[74:75], v[74:75], v[4:5], v[2:3] neg_lo:[0,0,1] neg_hi:[0,0,1]
	v_pk_fma_f32 v[60:61], v[60:61], v[4:5], v[0:1]
	global_load_dwordx4 v[0:3], v18, s[60:61] offset:48
	global_load_dwordx4 v[4:7], v18, s[60:61] offset:32
	global_load_dwordx4 v[8:11], v18, s[60:61] offset:16
	global_load_dwordx4 v[12:15], v18, s[60:61]
	s_waitcnt vmcnt(0)
	v_mov_b32_e32 v17, v14
	v_mov_b32_e32 v14, v13
	v_mov_b32_e32 v16, v12
	v_pk_mul_f32 v[12:13], v[80:81], v[14:15]
	v_pk_mul_f32 v[14:15], v[26:27], v[14:15]
	v_pk_fma_f32 v[26:27], v[26:27], v[16:17], v[12:13]
	v_mov_b32_e32 v13, v10
	v_mov_b32_e32 v10, v9
	v_mov_b32_e32 v12, v8
	v_pk_mul_f32 v[8:9], v[52:53], v[10:11]
	v_pk_mul_f32 v[10:11], v[40:41], v[10:11]
	v_pk_fma_f32 v[40:41], v[40:41], v[12:13], v[8:9]
	v_mov_b32_e32 v9, v6
	v_mov_b32_e32 v6, v5
	v_mov_b32_e32 v8, v4
	v_pk_mul_f32 v[4:5], v[54:55], v[6:7]
	v_pk_mul_f32 v[6:7], v[42:43], v[6:7]
	v_pk_fma_f32 v[42:43], v[42:43], v[8:9], v[4:5]
	v_mov_b32_e32 v5, v2
	v_mov_b32_e32 v2, v1
	v_mov_b32_e32 v4, v0
	v_pk_mul_f32 v[0:1], v[56:57], v[2:3]
	v_pk_mul_f32 v[2:3], v[50:51], v[2:3]
	v_pk_fma_f32 v[80:81], v[80:81], v[16:17], v[14:15] neg_lo:[0,0,1] neg_hi:[0,0,1]
	v_pk_fma_f32 v[52:53], v[52:53], v[12:13], v[10:11] neg_lo:[0,0,1] neg_hi:[0,0,1]
	v_pk_fma_f32 v[54:55], v[54:55], v[8:9], v[6:7] neg_lo:[0,0,1] neg_hi:[0,0,1]
	v_pk_fma_f32 v[56:57], v[56:57], v[4:5], v[2:3] neg_lo:[0,0,1] neg_hi:[0,0,1]
	v_pk_fma_f32 v[50:51], v[50:51], v[4:5], v[0:1]
	global_load_dwordx4 v[0:3], v18, s[60:61] offset:112
	global_load_dwordx4 v[4:7], v18, s[60:61] offset:96
	global_load_dwordx4 v[8:11], v18, s[60:61] offset:80
	global_load_dwordx4 v[12:15], v18, s[60:61] offset:64
	s_waitcnt vmcnt(0)
	v_mov_b32_e32 v17, v14
	v_mov_b32_e32 v14, v13
	v_mov_b32_e32 v16, v12
	v_pk_mul_f32 v[12:13], v[46:47], v[14:15]
	v_pk_mul_f32 v[14:15], v[32:33], v[14:15]
	v_pk_fma_f32 v[32:33], v[32:33], v[16:17], v[12:13]
	v_mov_b32_e32 v13, v10
	v_mov_b32_e32 v10, v9
	v_mov_b32_e32 v12, v8
	v_pk_mul_f32 v[8:9], v[62:63], v[10:11]
	v_pk_mul_f32 v[10:11], v[34:35], v[10:11]
	v_pk_fma_f32 v[34:35], v[34:35], v[12:13], v[8:9]
	v_mov_b32_e32 v9, v6
	v_mov_b32_e32 v6, v5
	v_mov_b32_e32 v8, v4
	v_pk_mul_f32 v[4:5], v[64:65], v[6:7]
	v_pk_mul_f32 v[6:7], v[36:37], v[6:7]
	v_pk_fma_f32 v[36:37], v[36:37], v[8:9], v[4:5]
	v_mov_b32_e32 v5, v2
	v_mov_b32_e32 v2, v1
	v_mov_b32_e32 v4, v0
	v_pk_mul_f32 v[0:1], v[66:67], v[2:3]
	v_pk_mul_f32 v[2:3], v[38:39], v[2:3]
	v_pk_fma_f32 v[46:47], v[46:47], v[16:17], v[14:15] neg_lo:[0,0,1] neg_hi:[0,0,1]
	v_pk_fma_f32 v[62:63], v[62:63], v[12:13], v[10:11] neg_lo:[0,0,1] neg_hi:[0,0,1]
	v_pk_fma_f32 v[64:65], v[64:65], v[8:9], v[6:7] neg_lo:[0,0,1] neg_hi:[0,0,1]
	v_pk_fma_f32 v[66:67], v[66:67], v[4:5], v[2:3] neg_lo:[0,0,1] neg_hi:[0,0,1]
	v_pk_fma_f32 v[38:39], v[38:39], v[4:5], v[0:1]
